# v39: v33 + static priority raise for waves 4-7 from the start of each GEMM phase (covers the skinny GEMMs; the main-loop flips reset it)
# baseline (speedup 1.0000x reference)
; #define LAS __attribute__((address_space(3)))
; __device__ __forceinline__ CArgs* phase_args() { CArgs* p = (CArgs*)__builtin_amdgcn_kernarg_segment_ptr(); asm volatile("" : "+s"(p)); return p; }
;     LAS float* red = (LAS float*)lds;
;     const int fr = lane & 15, fq = lane >> 4, kw = K / 8;
;     for (int item = bx; item < nct * nrh * (8 / RB); item += G) {
;         const int ct = item % nct, rs = item / nct, row0 = rs * RB * 16, rh = row0 >> 7, rin = row0 & 127;
;         f32x4 acc[RB];
; #pragma unroll
;         for (int rb = 0; rb < RB; ++rb) acc[rb] = (f32x4){0.f, 0.f, 0.f, 0.f};
;         const bf16_t* bp = Wt + (size_t)(ct * 16 + fr) * ldb + wave * kw + fq * 8;
;         const bf16_t* ap = A + (size_t)(row0 + fr) * lda + wave * kw + fq * 8;
;         bf16x8 b0 = *(const bf16x8*)(bp), b1 = *(const bf16x8*)(bp + 32), a0[RB], a1[RB];
; __global__ void __launch_bounds__(512, 2) mega_fwd(Args args) {
;     ...
;     if (IN(1)) { CArgs* pa = phase_args();
;         skinny_gemm(lds, H + (size_t)T * D, D, WT_IN, D, D, INW / 16, 1, bx, G, wave, lane, tid, SkBf16{PROJ + (size_t)T * INW, INW});
;         skinny_gemm<4>(lds, MN, D, WT_MKV, D, D, 1024 / 16, 2, bx, G, wave, lane, tid, SkF32{MEMKV, 1024});
.LBB0_111:
.LBB0_112:
	s_cmp_lt_i32 s24, 2
	s_cselect_b64 s[4:5], -1, 0
	s_cmp_gt_i32 s25, 1
	s_cselect_b64 s[6:7], -1, 0
	s_and_b64 s[4:5], s[4:5], s[6:7]
	s_andn2_b64 vcc, exec, s[4:5]
	s_cbranch_vccnz .LBB0_148
	s_cmp_ge_u32 s80, 4
	s_cbranch_scc0 .Lp1_prio_done
	s_setprio 1
.Lp1_prio_done:
	s_mov_b64 s[4:5], s[0:1]
	s_load_dwordx2 s[8:9], s[4:5], 0xf8
	s_waitcnt lgkmcnt(0)
	s_add_u32 s13, s8, 0x100000
	s_addc_u32 s15, s9, 0
	s_cmpk_lt_i32 s2, 0x100
	s_cbranch_scc1 .LBB0_115
	v_lshrrev_b32_e32 v6, 2, v193
	v_lshlrev_b32_e32 v9, 2, v193
	v_and_b32_e32 v8, 15, v193
	s_cbranch_execz .LBB0_116
	s_branch .LBB0_124

; #define LAS __attribute__((address_space(3)))
; __device__ __forceinline__ CArgs* phase_args() { CArgs* p = (CArgs*)__builtin_amdgcn_kernarg_segment_ptr(); asm volatile("" : "+s"(p)); return p; }
; __global__ void __launch_bounds__(512, 2) mega_fwd(Args args) {
;     ...
;     if (IN(5)) { CArgs* pa = phase_args();
;         skinny_gemm<4>(lds, MIXED + (size_t)T * D, D, WT_OUT, D, D, D / 16, 1, bx, G, wave, lane, tid, SkResN{x_sample, XRES + (size_t)T * D, H + (size_t)T * D, SSQ1 + T});
;         pg8::Gemm g{MIXED, WT_OUT, D, D, D, 0}; pg8::StaticOrder S; S.init(T, D, G, bx); pg8::EpiResN E{x_prompt, XRES, H, PSSQ1, (LAS float*)(lds + 131072)}; pg8::gemm_phase(lds, g, S, E); }
.LBB0_489:
.LBB0_490:
	s_cmp_lt_i32 s24, 6
	s_cselect_b64 s[4:5], -1, 0
	s_cmp_gt_i32 s25, 5
	s_cselect_b64 s[6:7], -1, 0
	s_and_b64 s[4:5], s[4:5], s[6:7]
	s_andn2_b64 vcc, exec, s[4:5]
	s_cbranch_vccnz .LBB0_543
	s_cmp_ge_u32 s80, 4
	s_cbranch_scc0 .Lp5_prio_done
	s_setprio 1
.Lp5_prio_done:
	s_mov_b64 s[8:9], s[0:1]
	s_load_dwordx2 s[10:11], s[8:9], 0xf8
	s_waitcnt lgkmcnt(0)
	s_add_u32 s27, s10, 0x1100000
	s_addc_u32 s33, s11, 0
	s_cmpk_lt_i32 s2, 0x100
	s_cbranch_scc1 .LBB0_493
	v_lshrrev_b32_e32 v6, 2, v193
	v_lshlrev_b32_e32 v9, 2, v193
	v_lshlrev_b32_e32 v8, 2, v196
	s_cbranch_execz .LBB0_494
	s_branch .LBB0_499

; #define LAS __attribute__((address_space(3)))
; __device__ __forceinline__ CArgs* phase_args() { CArgs* p = (CArgs*)__builtin_amdgcn_kernarg_segment_ptr(); asm volatile("" : "+s"(p)); return p; }
; __global__ void __launch_bounds__(512, 2) mega_fwd(Args args) {
;     ...
;     if (IN(9)) { CArgs* pa = phase_args();
;         skinny_gemm<4>(lds, OM + (size_t)T * MEMW, MEMW, WT_MO, MEMW, MEMW, D / 16, 1, bx, G, wave, lane, tid, SkResN{XRES + (size_t)T * D, XRES + (size_t)T * D, H + (size_t)T * D, SSQ2 + T});
;         pg8::Gemm g{OM, WT_MO, MEMW, MEMW, MEMW, 0}; pg8::StaticOrder S; S.init(T, D, G, bx); pg8::EpiResN E{XRES, XRES, H, PSSQ2, (LAS float*)(lds + 131072)}; pg8::gemm_phase(lds, g, S, E); }
.LBB0_697:
	s_cmp_lt_i32 s24, 10
	s_cselect_b64 s[4:5], -1, 0
	s_cmp_gt_i32 s25, 9
	s_cselect_b64 s[6:7], -1, 0
	s_and_b64 s[4:5], s[4:5], s[6:7]
	s_andn2_b64 vcc, exec, s[4:5]
	s_cbranch_vccnz .LBB0_750
	s_cmp_ge_u32 s80, 4
	s_cbranch_scc0 .Lp9_prio_done
	s_setprio 1
.Lp9_prio_done:
	s_mov_b64 s[4:5], s[0:1]
	s_load_dwordx2 s[8:9], s[4:5], 0xf8
	s_waitcnt lgkmcnt(0)
	s_add_u32 s27, s8, 0x1f00000
	s_addc_u32 s33, s9, 0
	s_cmpk_lt_i32 s2, 0x100
	s_cbranch_scc1 .LBB0_700
	v_lshrrev_b32_e32 v6, 2, v193
	v_lshlrev_b32_e32 v10, 2, v193
	v_lshlrev_b32_e32 v9, 2, v196
	v_mbcnt_lo_u32_b32 v8, -1, 0
	s_cbranch_execz .LBB0_701
	s_branch .LBB0_706

; #define LAS __attribute__((address_space(3)))
; __device__ __forceinline__ CArgs* phase_args() { CArgs* p = (CArgs*)__builtin_amdgcn_kernarg_segment_ptr(); asm volatile("" : "+s"(p)); return p; }
; template <int NT, class Epi>
; __device__ __forceinline__ void skinny_gemm_nt(LAS unsigned char* lds, const bf16_t* A, int lda, const bf16_t* Wt, int ldb, int K, int nct, int nrh, int bx, int G, int wave, int lane, int tid, const Epi& E) {
;     LAS float* red = (LAS float*)lds;
;     const int fr = lane & 15, fq = lane >> 4, kw = K / 8, ngrp = (nct + NT - 1) / NT;
;     for (int item = bx; item < ngrp * nrh; item += G) {
; __global__ void __launch_bounds__(512, 2) mega_fwd(Args args) {
;     ...
;     if (IN(11)) { CArgs* pa = phase_args();
;         skinny_gemm_nt<3>(lds, H + (size_t)T * D, D, WT_GU, D, D, 2 * FF / 16, 1, bx, G, wave, lane, tid, SkGU{GB + (size_t)T * FF, UPB + (size_t)T * FF, SSQ2 + T});
;         pg8::Gemm g{H, WT_GU, D, D, D, 0}; pg8::StaticOrder S; S.init(T, 2 * FF, G, bx); pg8::EpiGUConv E{UPB, PSSQ2, conv_w, conv_b, FIRSTG, FIRSTUP, LASTG, (LAS float*)(lds + 131072 + 4096)}; pg8::gemm_phase(lds, g, S, E); }
.LBB0_767:
	s_cmp_lt_i32 s24, 12
	s_cselect_b64 s[4:5], -1, 0
	s_cmp_gt_i32 s25, 11
	s_cselect_b64 s[6:7], -1, 0
	s_and_b64 s[4:5], s[4:5], s[6:7]
	s_andn2_b64 vcc, exec, s[4:5]
	s_cbranch_vccnz .LBB0_807
	s_cmp_ge_u32 s80, 4
	s_cbranch_scc0 .Lp11_prio_done
	s_setprio 1
.Lp11_prio_done:
	s_mov_b64 s[6:7], s[0:1]
	s_load_dwordx2 s[4:5], s[6:7], 0xf8
	s_waitcnt lgkmcnt(0)
	s_add_u32 s27, s4, 0x2100000
	s_addc_u32 s41, s5, 0
	s_cmpk_lt_i32 s2, 0xeb
	s_cbranch_scc1 .LBB0_770
	s_waitcnt vmcnt(0)
	v_lshrrev_b32_e32 v148, 2, v193
	v_lshlrev_b32_e32 v147, 2, v193
	v_lshlrev_b32_e32 v146, 2, v196
	s_cbranch_execz .LBB0_771
	s_branch .LBB0_775

; __device__ __forceinline__ CArgs* phase_args() { CArgs* p = (CArgs*)__builtin_amdgcn_kernarg_segment_ptr(); asm volatile("" : "+s"(p)); return p; }
; __global__ void __launch_bounds__(512, 2) mega_fwd(Args args) {
;     ...
;     if (IN(13)) { CArgs* pa = phase_args();
;         skinny_gemm<4>(lds, UPB + (size_t)T * FF, FF, WT_DN, FF, FF, D / 16, 1, bx, G, wave, lane, tid, SkRes{XRES + (size_t)T * D, out + (size_t)T * D});
;         pg8::Gemm g{UPB, WT_DN, FF, FF, FF, 0}; pg8::StaticOrder S; S.init(T, D, G, bx); pg8::EpiRes E{XRES, XRES, MP, out, T}; pg8::gemm_phase(lds, g, S, E); }
.LBB0_866:
	s_cmp_lt_i32 s24, 14
	s_cselect_b64 s[4:5], -1, 0
	s_cmp_gt_i32 s25, 13
	s_cselect_b64 s[6:7], -1, 0
	s_and_b64 s[4:5], s[4:5], s[6:7]
	s_andn2_b64 vcc, exec, s[4:5]
	s_cbranch_vccnz .LBB0_921
	s_cmp_ge_u32 s80, 4
	s_cbranch_scc0 .Lp13_prio_done
	s_setprio 1
.Lp13_prio_done:
	s_load_dwordx4 s[8:11], s[0:1], 0xf0
	v_lshlrev_b32_e32 v17, 2, v193
	s_waitcnt lgkmcnt(0)
	s_add_u32 s33, s10, 0x4d00000
	s_addc_u32 s34, s11, 0
	s_cmpk_lt_i32 s2, 0x100
	s_cbranch_scc1 .LBB0_869
	v_lshrrev_b32_e32 v0, 2, v193
	v_lshlrev_b32_e32 v8, 2, v193
	v_lshlrev_b32_e32 v16, 2, v196
	s_cbranch_execz .LBB0_870
	s_branch .LBB0_875
